# GEMM stream K-loop: s_setprio flips removed (16 instrs); x->bf16 loop de-serialized
# speedup vs baseline: 1.0080x; 1.0080x over previous
.LBB0_836:
	s_add_u32 s19, s90, s12
	s_addc_u32 s20, s91, s13
	s_and_b64 s[16:17], s[14:15], exec
	s_cselect_b32 s17, s45, s20
	s_cselect_b32 s16, s44, s19
	s_add_u32 s19, s52, s12
	s_addc_u32 s20, s53, s13
	s_lshl_b64 s[24:25], s[40:41], 7
	s_and_b64 s[14:15], s[14:15], exec
	s_cselect_b32 s15, s93, s20
	s_cselect_b32 s14, s92, s19
	s_cselect_b32 s20, s25, s7
	s_cselect_b32 s21, s24, s6
	s_add_i32 s24, 0, 0x10000
	v_add_u32_e32 v2, s24, v252
	s_add_i32 s25, 0, 0x14000
	ds_read_b128 v[144:147], v2
	ds_read_b128 v[148:151], v2 offset:1024
	ds_read_b128 v[152:155], v2 offset:2048
	ds_read_b128 v[156:159], v2 offset:3072
	v_add_u32_e32 v2, s25, v252
	ds_read_b128 v[160:163], v2
	ds_read_b128 v[164:167], v2 offset:1024
	ds_read_b128 v[168:171], v2 offset:2048
	ds_read_b128 v[172:175], v2 offset:3072
	s_mov_b32 s19, s41
	v_lshl_add_u64 v[236:237], s[90:91], 0, v[134:135]
	s_add_i32 m0, s78, 0xc000
	ds_read_b128 v[176:179], v229
	ds_read_b128 v[180:183], v229 offset:1024
	ds_read_b128 v[184:187], v229 offset:2048
	ds_read_b128 v[204:207], v229 offset:3072
	ds_read_b128 v[208:211], v229 offset:4096
	ds_read_b128 v[212:215], v229 offset:5120
	ds_read_b128 v[224:227], v229 offset:6144
	ds_read_b128 v[216:219], v229 offset:7168
	global_load_lds_dwordx4 v[236:237], off
	v_lshl_add_u64 v[236:237], s[90:91], 0, v[4:5]
	s_add_i32 m0, s78, 0xe000
	s_nop 0
	global_load_lds_dwordx4 v[236:237], off
	s_waitcnt vmcnt(8)
	s_waitcnt lgkmcnt(0)
	s_barrier
	s_waitcnt lgkmcnt(0)
	v_mfma_f32_16x16x32_bf16 v[126:129], v[144:147], v[176:179], v[126:129]
	v_mfma_f32_16x16x32_bf16 v[130:133], v[152:155], v[176:179], v[130:133]
	v_mfma_f32_16x16x32_bf16 v[118:121], v[144:147], v[184:187], v[118:121]
	v_mfma_f32_16x16x32_bf16 v[122:125], v[152:155], v[184:187], v[122:125]
	v_mfma_f32_16x16x32_bf16 v[110:113], v[144:147], v[208:211], v[110:113]
	v_mfma_f32_16x16x32_bf16 v[114:117], v[152:155], v[208:211], v[114:117]
	v_mfma_f32_16x16x32_bf16 v[102:105], v[144:147], v[224:227], v[102:105]
	v_mfma_f32_16x16x32_bf16 v[106:109], v[152:155], v[224:227], v[106:109]
	v_mfma_f32_16x16x32_bf16 v[126:129], v[148:151], v[180:183], v[126:129]
	v_mfma_f32_16x16x32_bf16 v[130:133], v[156:159], v[180:183], v[130:133]
	v_mfma_f32_16x16x32_bf16 v[118:121], v[148:151], v[204:207], v[118:121]
	v_mfma_f32_16x16x32_bf16 v[122:125], v[156:159], v[204:207], v[122:125]
	v_mfma_f32_16x16x32_bf16 v[110:113], v[148:151], v[212:215], v[110:113]
	v_mfma_f32_16x16x32_bf16 v[114:117], v[156:159], v[212:215], v[114:117]
	v_mfma_f32_16x16x32_bf16 v[102:105], v[148:151], v[216:219], v[102:105]
	v_mfma_f32_16x16x32_bf16 v[106:109], v[156:159], v[216:219], v[106:109]
	v_mfma_f32_16x16x32_bf16 v[94:97], v[160:163], v[176:179], v[94:97]
	v_mfma_f32_16x16x32_bf16 v[98:101], v[168:171], v[176:179], v[98:101]
	v_mfma_f32_16x16x32_bf16 v[86:89], v[160:163], v[184:187], v[86:89]
	v_mfma_f32_16x16x32_bf16 v[90:93], v[168:171], v[184:187], v[90:93]
	v_mfma_f32_16x16x32_bf16 v[78:81], v[160:163], v[208:211], v[78:81]
	v_mfma_f32_16x16x32_bf16 v[82:85], v[168:171], v[208:211], v[82:85]
	v_mfma_f32_16x16x32_bf16 v[70:73], v[160:163], v[224:227], v[70:73]
	v_mfma_f32_16x16x32_bf16 v[74:77], v[168:171], v[224:227], v[74:77]
	v_mfma_f32_16x16x32_bf16 v[94:97], v[164:167], v[180:183], v[94:97]
	v_mfma_f32_16x16x32_bf16 v[98:101], v[172:175], v[180:183], v[98:101]
	v_mfma_f32_16x16x32_bf16 v[86:89], v[164:167], v[204:207], v[86:89]
	v_mfma_f32_16x16x32_bf16 v[90:93], v[172:175], v[204:207], v[90:93]
	v_mfma_f32_16x16x32_bf16 v[78:81], v[164:167], v[212:215], v[78:81]
	v_mfma_f32_16x16x32_bf16 v[82:85], v[172:175], v[212:215], v[82:85]
	v_mfma_f32_16x16x32_bf16 v[70:73], v[164:167], v[216:219], v[70:73]
	v_mfma_f32_16x16x32_bf16 v[74:77], v[172:175], v[216:219], v[74:77]
	s_barrier
	s_add_i32 s24, s24, s5
	s_mov_b32 m0, s24
	ds_read_b128 v[176:179], v229 offset:16384
	ds_read_b128 v[180:183], v229 offset:17408
	ds_read_b128 v[184:187], v229 offset:18432
	ds_read_b128 v[204:207], v229 offset:19456
	ds_read_b128 v[208:211], v229 offset:20480
	ds_read_b128 v[212:215], v229 offset:21504
	ds_read_b128 v[216:219], v229 offset:22528
	ds_read_b128 v[224:227], v229 offset:23552
	v_mov_b32_e32 v143, v3
	global_load_lds_dwordx4 v142, s[14:15]
	v_mov_b32_e32 v141, v3
	s_add_i32 m0, s24, 0x2000
	s_lshl_b64 s[18:19], s[18:19], 7
	v_lshl_add_u64 v[236:237], s[14:15], 0, v[142:143]
	v_lshl_add_u64 v[222:223], s[14:15], 0, v[140:141]
	global_load_lds_dwordx4 v140, s[14:15]
	s_add_u32 s14, s14, s18
	s_addc_u32 s15, s15, s19
	s_add_i32 s18, s25, s5
	s_mov_b32 m0, s18
	v_lshl_add_u64 v[250:251], s[16:17], 0, v[138:139]
	global_load_lds_dwordx4 v142, s[14:15]
	s_add_i32 m0, s18, 0x2000
	v_lshl_add_u64 v[232:233], s[16:17], 0, v[136:137]
	global_load_lds_dwordx4 v140, s[14:15]
	s_mov_b32 m0, s78
	v_lshl_add_u64 v[244:245], s[14:15], 0, v[142:143]
	global_load_lds_dwordx4 v[250:251], off
	s_mov_b32 m0, s87
	v_lshl_add_u64 v[246:247], s[14:15], 0, v[140:141]
	global_load_lds_dwordx4 v[232:233], off
	s_waitcnt vmcnt(8)
	s_waitcnt lgkmcnt(0)
	s_barrier
	s_waitcnt lgkmcnt(0)
	v_mfma_f32_16x16x32_bf16 v[46:49], v[144:147], v[176:179], v[46:49]
	v_mfma_f32_16x16x32_bf16 v[50:53], v[152:155], v[176:179], v[50:53]
	v_mfma_f32_16x16x32_bf16 v[38:41], v[144:147], v[184:187], v[38:41]
	v_mfma_f32_16x16x32_bf16 v[42:45], v[152:155], v[184:187], v[42:45]
	v_mfma_f32_16x16x32_bf16 v[30:33], v[144:147], v[208:211], v[30:33]
	v_mfma_f32_16x16x32_bf16 v[34:37], v[152:155], v[208:211], v[34:37]
	v_mfma_f32_16x16x32_bf16 v[22:25], v[144:147], v[216:219], v[22:25]
	v_mfma_f32_16x16x32_bf16 v[26:29], v[152:155], v[216:219], v[26:29]
	v_mfma_f32_16x16x32_bf16 v[46:49], v[148:151], v[180:183], v[46:49]
	v_mfma_f32_16x16x32_bf16 v[50:53], v[156:159], v[180:183], v[50:53]
	v_mfma_f32_16x16x32_bf16 v[38:41], v[148:151], v[204:207], v[38:41]
	v_mfma_f32_16x16x32_bf16 v[42:45], v[156:159], v[204:207], v[42:45]
	v_mfma_f32_16x16x32_bf16 v[30:33], v[148:151], v[212:215], v[30:33]
	v_mfma_f32_16x16x32_bf16 v[34:37], v[156:159], v[212:215], v[34:37]
	v_mfma_f32_16x16x32_bf16 v[22:25], v[148:151], v[224:227], v[22:25]
	v_mfma_f32_16x16x32_bf16 v[26:29], v[156:159], v[224:227], v[26:29]
	v_mfma_f32_16x16x32_bf16 v[14:17], v[160:163], v[176:179], v[14:17]
	v_mfma_f32_16x16x32_bf16 v[18:21], v[168:171], v[176:179], v[18:21]
	v_mfma_f32_16x16x32_bf16 v[6:9], v[160:163], v[184:187], v[6:9]
	v_mfma_f32_16x16x32_bf16 v[10:13], v[168:171], v[184:187], v[10:13]
	v_mfma_f32_16x16x32_bf16 v[54:57], v[160:163], v[208:211], v[54:57]
	v_mfma_f32_16x16x32_bf16 v[62:65], v[168:171], v[208:211], v[62:65]
	v_mfma_f32_16x16x32_bf16 v[58:61], v[160:163], v[216:219], v[58:61]
	v_mfma_f32_16x16x32_bf16 v[66:69], v[168:171], v[216:219], v[66:69]
	v_mfma_f32_16x16x32_bf16 v[14:17], v[164:167], v[180:183], v[14:17]
	v_mfma_f32_16x16x32_bf16 v[18:21], v[172:175], v[180:183], v[18:21]
	v_mfma_f32_16x16x32_bf16 v[6:9], v[164:167], v[204:207], v[6:9]
	v_mfma_f32_16x16x32_bf16 v[10:13], v[172:175], v[204:207], v[10:13]
	v_mfma_f32_16x16x32_bf16 v[54:57], v[164:167], v[212:215], v[54:57]
	v_mfma_f32_16x16x32_bf16 v[62:65], v[172:175], v[212:215], v[62:65]
	v_mfma_f32_16x16x32_bf16 v[58:61], v[164:167], v[224:227], v[58:61]
	v_mfma_f32_16x16x32_bf16 v[66:69], v[172:175], v[224:227], v[66:69]
	s_barrier
	s_add_i32 s18, 0, 0x18000
	v_add_u32_e32 v2, s18, v252
	s_add_i32 s19, 0, 0x1c000
	ds_read_b128 v[140:143], v2
	ds_read_b128 v[144:147], v2 offset:1024
	ds_read_b128 v[148:151], v2 offset:2048
	ds_read_b128 v[152:155], v2 offset:3072
	v_add_u32_e32 v2, s19, v252
	ds_read_b128 v[156:159], v2
	ds_read_b128 v[160:163], v2 offset:1024
	ds_read_b128 v[164:167], v2 offset:2048
	ds_read_b128 v[168:171], v2 offset:3072
	s_add_u32 s14, s16, s21
	s_addc_u32 s15, s17, s20
	s_mov_b32 m0, s79
	v_lshl_add_u64 v[138:139], s[14:15], 0, v[138:139]
	ds_read_b128 v[172:175], v229 offset:32768
	ds_read_b128 v[176:179], v229 offset:33792
	ds_read_b128 v[180:183], v229 offset:34816
	ds_read_b128 v[184:187], v229 offset:35840
	ds_read_b128 v[204:207], v229 offset:36864
	ds_read_b128 v[208:211], v229 offset:37888
	ds_read_b128 v[212:215], v229 offset:38912
	ds_read_b128 v[216:219], v229 offset:39936
	global_load_lds_dwordx4 v[138:139], off
	v_lshl_add_u64 v[136:137], s[14:15], 0, v[136:137]
	s_mov_b32 m0, s34
	s_nop 0
	global_load_lds_dwordx4 v[136:137], off
	s_waitcnt vmcnt(8)
	s_waitcnt lgkmcnt(0)
	s_barrier
	s_waitcnt lgkmcnt(0)
	v_mfma_f32_16x16x32_bf16 v[126:129], v[140:143], v[172:175], v[126:129]
	v_mfma_f32_16x16x32_bf16 v[130:133], v[148:151], v[172:175], v[130:133]
	v_mfma_f32_16x16x32_bf16 v[118:121], v[140:143], v[180:183], v[118:121]
	v_mfma_f32_16x16x32_bf16 v[122:125], v[148:151], v[180:183], v[122:125]
	v_mfma_f32_16x16x32_bf16 v[110:113], v[140:143], v[204:207], v[110:113]
	v_mfma_f32_16x16x32_bf16 v[114:117], v[148:151], v[204:207], v[114:117]
	v_mfma_f32_16x16x32_bf16 v[102:105], v[140:143], v[212:215], v[102:105]
	v_mfma_f32_16x16x32_bf16 v[106:109], v[148:151], v[212:215], v[106:109]
	v_mfma_f32_16x16x32_bf16 v[126:129], v[144:147], v[176:179], v[126:129]
	v_mfma_f32_16x16x32_bf16 v[130:133], v[152:155], v[176:179], v[130:133]
	v_mfma_f32_16x16x32_bf16 v[118:121], v[144:147], v[184:187], v[118:121]
	v_mfma_f32_16x16x32_bf16 v[122:125], v[152:155], v[184:187], v[122:125]
	v_mfma_f32_16x16x32_bf16 v[110:113], v[144:147], v[208:211], v[110:113]
	v_mfma_f32_16x16x32_bf16 v[114:117], v[152:155], v[208:211], v[114:117]
	v_mfma_f32_16x16x32_bf16 v[102:105], v[144:147], v[216:219], v[102:105]
	v_mfma_f32_16x16x32_bf16 v[106:109], v[152:155], v[216:219], v[106:109]
	v_mfma_f32_16x16x32_bf16 v[94:97], v[156:159], v[172:175], v[94:97]
	v_mfma_f32_16x16x32_bf16 v[98:101], v[164:167], v[172:175], v[98:101]
	v_mfma_f32_16x16x32_bf16 v[86:89], v[156:159], v[180:183], v[86:89]
	v_mfma_f32_16x16x32_bf16 v[90:93], v[164:167], v[180:183], v[90:93]
	v_mfma_f32_16x16x32_bf16 v[78:81], v[156:159], v[204:207], v[78:81]
	v_mfma_f32_16x16x32_bf16 v[82:85], v[164:167], v[204:207], v[82:85]
	v_mfma_f32_16x16x32_bf16 v[70:73], v[156:159], v[212:215], v[70:73]
	v_mfma_f32_16x16x32_bf16 v[74:77], v[164:167], v[212:215], v[74:77]
	v_mfma_f32_16x16x32_bf16 v[94:97], v[160:163], v[176:179], v[94:97]
	v_mfma_f32_16x16x32_bf16 v[98:101], v[168:171], v[176:179], v[98:101]
	v_mfma_f32_16x16x32_bf16 v[86:89], v[160:163], v[184:187], v[86:89]
	v_mfma_f32_16x16x32_bf16 v[90:93], v[168:171], v[184:187], v[90:93]
	v_mfma_f32_16x16x32_bf16 v[78:81], v[160:163], v[208:211], v[78:81]
	v_mfma_f32_16x16x32_bf16 v[82:85], v[168:171], v[208:211], v[82:85]
	v_mfma_f32_16x16x32_bf16 v[70:73], v[160:163], v[216:219], v[70:73]
	v_mfma_f32_16x16x32_bf16 v[74:77], v[168:171], v[216:219], v[74:77]
	s_barrier
	s_add_i32 s14, s18, s5
	v_lshl_add_u64 v[216:217], v[236:237], 0, s[60:61]
	s_mov_b32 m0, s14
	ds_read_b128 v[136:139], v229 offset:49152
	ds_read_b128 v[172:175], v229 offset:50176
	ds_read_b128 v[176:179], v229 offset:51200
	ds_read_b128 v[180:183], v229 offset:52224
	ds_read_b128 v[184:187], v229 offset:53248
	ds_read_b128 v[204:207], v229 offset:54272
	ds_read_b128 v[208:211], v229 offset:55296
	ds_read_b128 v[212:215], v229 offset:56320
	global_load_lds_dwordx4 v[216:217], off
	v_lshl_add_u64 v[216:217], v[222:223], 0, s[60:61]
	s_add_i32 m0, s14, 0x2000
	s_add_i32 s14, s19, s5
	global_load_lds_dwordx4 v[216:217], off
	v_lshl_add_u64 v[216:217], v[244:245], 0, s[60:61]
	s_mov_b32 m0, s14
	s_nop 0
	global_load_lds_dwordx4 v[216:217], off
	v_lshl_add_u64 v[216:217], v[246:247], 0, s[60:61]
	s_add_i32 m0, s14, 0x2000
	s_nop 0
	global_load_lds_dwordx4 v[216:217], off
	v_lshl_add_u64 v[216:217], v[250:251], 0, s[60:61]
	s_mov_b32 m0, s35
	s_nop 0
	global_load_lds_dwordx4 v[216:217], off
	v_lshl_add_u64 v[216:217], v[232:233], 0, s[60:61]
	s_mov_b32 m0, s46
	s_nop 0
	global_load_lds_dwordx4 v[216:217], off
	s_waitcnt vmcnt(8)
	s_waitcnt lgkmcnt(0)
	s_barrier
	s_waitcnt lgkmcnt(0)
	v_mfma_f32_16x16x32_bf16 v[46:49], v[140:143], v[136:139], v[46:49]
	v_mfma_f32_16x16x32_bf16 v[50:53], v[148:151], v[136:139], v[50:53]
	v_mfma_f32_16x16x32_bf16 v[38:41], v[140:143], v[176:179], v[38:41]
	v_mfma_f32_16x16x32_bf16 v[42:45], v[148:151], v[176:179], v[42:45]
	v_mfma_f32_16x16x32_bf16 v[30:33], v[140:143], v[184:187], v[30:33]
	v_mfma_f32_16x16x32_bf16 v[34:37], v[148:151], v[184:187], v[34:37]
	v_mfma_f32_16x16x32_bf16 v[22:25], v[140:143], v[208:211], v[22:25]
	v_mfma_f32_16x16x32_bf16 v[26:29], v[148:151], v[208:211], v[26:29]
	v_mfma_f32_16x16x32_bf16 v[46:49], v[144:147], v[172:175], v[46:49]
	v_mfma_f32_16x16x32_bf16 v[50:53], v[152:155], v[172:175], v[50:53]
	v_mfma_f32_16x16x32_bf16 v[38:41], v[144:147], v[180:183], v[38:41]
	v_mfma_f32_16x16x32_bf16 v[42:45], v[152:155], v[180:183], v[42:45]
	v_mfma_f32_16x16x32_bf16 v[30:33], v[144:147], v[204:207], v[30:33]
	v_mfma_f32_16x16x32_bf16 v[34:37], v[152:155], v[204:207], v[34:37]
	v_mfma_f32_16x16x32_bf16 v[22:25], v[144:147], v[212:215], v[22:25]
	v_mfma_f32_16x16x32_bf16 v[26:29], v[152:155], v[212:215], v[26:29]
	v_mfma_f32_16x16x32_bf16 v[14:17], v[156:159], v[136:139], v[14:17]
	v_mfma_f32_16x16x32_bf16 v[18:21], v[164:167], v[136:139], v[18:21]
	v_mfma_f32_16x16x32_bf16 v[6:9], v[156:159], v[176:179], v[6:9]
	v_mfma_f32_16x16x32_bf16 v[10:13], v[164:167], v[176:179], v[10:13]
	v_mfma_f32_16x16x32_bf16 v[54:57], v[156:159], v[184:187], v[54:57]
	v_mfma_f32_16x16x32_bf16 v[62:65], v[164:167], v[184:187], v[62:65]
	v_mfma_f32_16x16x32_bf16 v[58:61], v[156:159], v[208:211], v[58:61]
	v_mfma_f32_16x16x32_bf16 v[66:69], v[164:167], v[208:211], v[66:69]
	v_mfma_f32_16x16x32_bf16 v[14:17], v[160:163], v[172:175], v[14:17]
	v_mfma_f32_16x16x32_bf16 v[18:21], v[168:171], v[172:175], v[18:21]
	v_mfma_f32_16x16x32_bf16 v[6:9], v[160:163], v[180:183], v[6:9]
	v_mfma_f32_16x16x32_bf16 v[10:13], v[168:171], v[180:183], v[10:13]
	v_mfma_f32_16x16x32_bf16 v[54:57], v[160:163], v[204:207], v[54:57]
	v_mfma_f32_16x16x32_bf16 v[62:65], v[168:171], v[204:207], v[62:65]
	v_mfma_f32_16x16x32_bf16 v[58:61], v[160:163], v[212:215], v[58:61]
	v_mfma_f32_16x16x32_bf16 v[66:69], v[168:171], v[212:215], v[66:69]
	s_barrier
	s_add_i32 s14, s63, 2
	s_add_u32 s12, s12, 0x100
	s_addc_u32 s13, s13, 0
	v_lshl_add_u64 v[4:5], v[4:5], 0, s[68:69]
	s_cmp_ge_i32 s63, s47
	v_lshl_add_u64 v[134:135], v[134:135], 0, s[68:69]
	s_cbranch_scc1 .LBB0_857
	s_mov_b32 s63, s14
	s_branch .LBB0_813
